# proj/gate-up epilogues no longer aligned between the two wave halves (template's default one-barrier offset kept through the epilogue)
# speedup vs baseline: 1.0064x; 1.0012x over previous
.LBB0_342:
	s_add_u32 s33, s44, 0xfff80080
	s_addc_u32 s43, s45, -1
	s_add_i32 s50, 0, 0x10000
	s_cmp_eq_u32 s35, 28
	s_cselect_b32 s49, s27, s43
	s_cselect_b32 s48, s28, s33
	v_add_u32_e32 v142, s50, v149
	s_cselect_b32 s47, s25, s34
	s_cselect_b32 s46, s29, s31
	s_add_i32 s33, 0, 0x14000
	ds_read_b128 v[154:157], v142
	ds_read_b128 v[168:171], v142 offset:1024
	ds_read_b128 v[172:175], v142 offset:2048
	ds_read_b128 v[176:179], v142 offset:3072
	v_add_u32_e32 v142, s33, v149
	ds_read_b128 v[180:183], v142
	ds_read_b128 v[184:187], v142 offset:1024
	ds_read_b128 v[188:191], v142 offset:2048
	ds_read_b128 v[192:195], v142 offset:3072
	s_add_i32 m0, s12, 0xc000
	ds_read_b128 v[196:199], v167
	ds_read_b128 v[200:203], v167 offset:1024
	ds_read_b128 v[204:207], v167 offset:2048
	ds_read_b128 v[208:211], v167 offset:3072
	ds_read_b128 v[212:215], v167 offset:4096
	ds_read_b128 v[216:219], v167 offset:5120
	ds_read_b128 v[220:223], v167 offset:6144
	ds_read_b128 v[224:227], v167 offset:7168
	global_load_lds_dwordx4 v140, s[44:45]
	s_add_i32 m0, s12, 0xe000
	s_nop 0
	global_load_lds_dwordx4 v138, s[44:45]
	s_waitcnt vmcnt(8)
	s_waitcnt lgkmcnt(0)
	s_barrier
	s_setprio 1
	s_waitcnt lgkmcnt(0)
	v_mfma_f32_16x16x32_bf16 v[128:131], v[154:157], v[196:199], v[128:131]
	v_mfma_f32_16x16x32_bf16 v[124:127], v[172:175], v[196:199], v[124:127]
	v_mfma_f32_16x16x32_bf16 v[116:119], v[154:157], v[204:207], v[116:119]
	v_mfma_f32_16x16x32_bf16 v[108:111], v[172:175], v[204:207], v[108:111]
	v_mfma_f32_16x16x32_bf16 v[100:103], v[154:157], v[212:215], v[100:103]
	v_mfma_f32_16x16x32_bf16 v[92:95], v[172:175], v[212:215], v[92:95]
	v_mfma_f32_16x16x32_bf16 v[84:87], v[154:157], v[220:223], v[84:87]
	v_mfma_f32_16x16x32_bf16 v[76:79], v[172:175], v[220:223], v[76:79]
	v_mfma_f32_16x16x32_bf16 v[128:131], v[168:171], v[200:203], v[128:131]
	v_mfma_f32_16x16x32_bf16 v[124:127], v[176:179], v[200:203], v[124:127]
	v_mfma_f32_16x16x32_bf16 v[116:119], v[168:171], v[208:211], v[116:119]
	v_mfma_f32_16x16x32_bf16 v[108:111], v[176:179], v[208:211], v[108:111]
	v_mfma_f32_16x16x32_bf16 v[100:103], v[168:171], v[216:219], v[100:103]
	v_mfma_f32_16x16x32_bf16 v[92:95], v[176:179], v[216:219], v[92:95]
	v_mfma_f32_16x16x32_bf16 v[84:87], v[168:171], v[224:227], v[84:87]
	v_mfma_f32_16x16x32_bf16 v[76:79], v[176:179], v[224:227], v[76:79]
	v_mfma_f32_16x16x32_bf16 v[120:123], v[180:183], v[196:199], v[120:123]
	v_mfma_f32_16x16x32_bf16 v[112:115], v[188:191], v[196:199], v[112:115]
	v_mfma_f32_16x16x32_bf16 v[104:107], v[180:183], v[204:207], v[104:107]
	v_mfma_f32_16x16x32_bf16 v[96:99], v[188:191], v[204:207], v[96:99]
	v_mfma_f32_16x16x32_bf16 v[88:91], v[180:183], v[212:215], v[88:91]
	v_mfma_f32_16x16x32_bf16 v[80:83], v[188:191], v[212:215], v[80:83]
	v_mfma_f32_16x16x32_bf16 v[72:75], v[180:183], v[220:223], v[72:75]
	v_mfma_f32_16x16x32_bf16 v[68:71], v[188:191], v[220:223], v[68:71]
	v_mfma_f32_16x16x32_bf16 v[120:123], v[184:187], v[200:203], v[120:123]
	v_mfma_f32_16x16x32_bf16 v[112:115], v[192:195], v[200:203], v[112:115]
	v_mfma_f32_16x16x32_bf16 v[104:107], v[184:187], v[208:211], v[104:107]
	v_mfma_f32_16x16x32_bf16 v[96:99], v[192:195], v[208:211], v[96:99]
	v_mfma_f32_16x16x32_bf16 v[88:91], v[184:187], v[216:219], v[88:91]
	v_mfma_f32_16x16x32_bf16 v[80:83], v[192:195], v[216:219], v[80:83]
	v_mfma_f32_16x16x32_bf16 v[72:75], v[184:187], v[224:227], v[72:75]
	v_mfma_f32_16x16x32_bf16 v[68:71], v[192:195], v[224:227], v[68:71]
	s_setprio 0
	s_barrier
	s_add_i32 s43, s50, s10
	s_mov_b32 m0, s43
	ds_read_b128 v[196:199], v167 offset:16384
	ds_read_b128 v[200:203], v167 offset:17408
	ds_read_b128 v[204:207], v167 offset:18432
	ds_read_b128 v[208:211], v167 offset:19456
	ds_read_b128 v[212:215], v167 offset:20480
	ds_read_b128 v[216:219], v167 offset:21504
	ds_read_b128 v[220:223], v167 offset:22528
	ds_read_b128 v[224:227], v167 offset:23552
	global_load_lds_dwordx4 v2, s[46:47]
	s_add_i32 m0, s43, 0x2000
	s_add_u32 s50, s46, 0x80000
	s_addc_u32 s51, s47, 0
	s_add_i32 s33, s33, s10
	global_load_lds_dwordx4 v0, s[46:47]
	s_mov_b32 m0, s33
	s_nop 0
	global_load_lds_dwordx4 v2, s[50:51]
	s_add_i32 m0, s33, 0x2000
	s_nop 0
	global_load_lds_dwordx4 v0, s[50:51]
	s_mov_b32 m0, s12
	s_nop 0
	global_load_lds_dwordx4 v134, s[48:49]
	s_mov_b32 m0, s13
	s_nop 0
	global_load_lds_dwordx4 v132, s[48:49]
	s_waitcnt vmcnt(8)
	s_waitcnt lgkmcnt(0)
	s_barrier
	s_setprio 1
	s_waitcnt lgkmcnt(0)
	v_mfma_f32_16x16x32_bf16 v[64:67], v[154:157], v[196:199], v[64:67]
	v_mfma_f32_16x16x32_bf16 v[60:63], v[172:175], v[196:199], v[60:63]
	v_mfma_f32_16x16x32_bf16 v[52:55], v[154:157], v[204:207], v[52:55]
	v_mfma_f32_16x16x32_bf16 v[44:47], v[172:175], v[204:207], v[44:47]
	v_mfma_f32_16x16x32_bf16 v[36:39], v[154:157], v[212:215], v[36:39]
	v_mfma_f32_16x16x32_bf16 v[28:31], v[172:175], v[212:215], v[28:31]
	v_mfma_f32_16x16x32_bf16 v[20:23], v[154:157], v[220:223], v[20:23]
	v_mfma_f32_16x16x32_bf16 v[12:15], v[172:175], v[220:223], v[12:15]
	v_mfma_f32_16x16x32_bf16 v[64:67], v[168:171], v[200:203], v[64:67]
	v_mfma_f32_16x16x32_bf16 v[60:63], v[176:179], v[200:203], v[60:63]
	v_mfma_f32_16x16x32_bf16 v[52:55], v[168:171], v[208:211], v[52:55]
	v_mfma_f32_16x16x32_bf16 v[44:47], v[176:179], v[208:211], v[44:47]
	v_mfma_f32_16x16x32_bf16 v[36:39], v[168:171], v[216:219], v[36:39]
	v_mfma_f32_16x16x32_bf16 v[28:31], v[176:179], v[216:219], v[28:31]
	v_mfma_f32_16x16x32_bf16 v[20:23], v[168:171], v[224:227], v[20:23]
	v_mfma_f32_16x16x32_bf16 v[12:15], v[176:179], v[224:227], v[12:15]
	v_mfma_f32_16x16x32_bf16 v[56:59], v[180:183], v[196:199], v[56:59]
	v_mfma_f32_16x16x32_bf16 v[48:51], v[188:191], v[196:199], v[48:51]
	v_mfma_f32_16x16x32_bf16 v[40:43], v[180:183], v[204:207], v[40:43]
	v_mfma_f32_16x16x32_bf16 v[32:35], v[188:191], v[204:207], v[32:35]
	v_mfma_f32_16x16x32_bf16 v[24:27], v[180:183], v[212:215], v[24:27]
	v_mfma_f32_16x16x32_bf16 v[16:19], v[188:191], v[212:215], v[16:19]
	v_mfma_f32_16x16x32_bf16 v[8:11], v[180:183], v[220:223], v[8:11]
	v_mfma_f32_16x16x32_bf16 v[4:7], v[188:191], v[220:223], v[4:7]
	v_mfma_f32_16x16x32_bf16 v[56:59], v[184:187], v[200:203], v[56:59]
	v_mfma_f32_16x16x32_bf16 v[48:51], v[192:195], v[200:203], v[48:51]
	v_mfma_f32_16x16x32_bf16 v[40:43], v[184:187], v[208:211], v[40:43]
	v_mfma_f32_16x16x32_bf16 v[32:35], v[192:195], v[208:211], v[32:35]
	v_mfma_f32_16x16x32_bf16 v[24:27], v[184:187], v[216:219], v[24:27]
	v_mfma_f32_16x16x32_bf16 v[16:19], v[192:195], v[216:219], v[16:19]
	v_mfma_f32_16x16x32_bf16 v[8:11], v[184:187], v[224:227], v[8:11]
	v_mfma_f32_16x16x32_bf16 v[4:7], v[192:195], v[224:227], v[4:7]
	s_setprio 0
	s_barrier
	s_add_i32 s33, 0, 0x18000
	v_add_u32_e32 v144, s33, v149
	s_add_i32 s43, 0, 0x1c000
	ds_read_b128 v[154:157], v144
	ds_read_b128 v[168:171], v144 offset:1024
	ds_read_b128 v[172:175], v144 offset:2048
	ds_read_b128 v[176:179], v144 offset:3072
	v_add_u32_e32 v144, s43, v149
	ds_read_b128 v[180:183], v144
	ds_read_b128 v[184:187], v144 offset:1024
	ds_read_b128 v[188:191], v144 offset:2048
	ds_read_b128 v[192:195], v144 offset:3072
	s_add_u32 s48, s48, 0x80000
	s_addc_u32 s49, s49, 0
	s_mov_b32 m0, s14
	ds_read_b128 v[196:199], v167 offset:32768
	ds_read_b128 v[200:203], v167 offset:33792
	ds_read_b128 v[204:207], v167 offset:34816
	ds_read_b128 v[208:211], v167 offset:35840
	ds_read_b128 v[212:215], v167 offset:36864
	ds_read_b128 v[216:219], v167 offset:37888
	ds_read_b128 v[220:223], v167 offset:38912
	ds_read_b128 v[224:227], v167 offset:39936
	global_load_lds_dwordx4 v134, s[48:49]
	s_mov_b32 m0, s15
	s_nop 0
	global_load_lds_dwordx4 v132, s[48:49]
	s_waitcnt vmcnt(8)
	s_waitcnt lgkmcnt(0)
	s_barrier
	s_setprio 1
	s_waitcnt lgkmcnt(0)
	v_mfma_f32_16x16x32_bf16 v[128:131], v[154:157], v[196:199], v[128:131]
	v_mfma_f32_16x16x32_bf16 v[124:127], v[172:175], v[196:199], v[124:127]
	v_mfma_f32_16x16x32_bf16 v[116:119], v[154:157], v[204:207], v[116:119]
	v_mfma_f32_16x16x32_bf16 v[108:111], v[172:175], v[204:207], v[108:111]
	v_mfma_f32_16x16x32_bf16 v[100:103], v[154:157], v[212:215], v[100:103]
	v_mfma_f32_16x16x32_bf16 v[92:95], v[172:175], v[212:215], v[92:95]
	v_mfma_f32_16x16x32_bf16 v[84:87], v[154:157], v[220:223], v[84:87]
	v_mfma_f32_16x16x32_bf16 v[76:79], v[172:175], v[220:223], v[76:79]
	v_mfma_f32_16x16x32_bf16 v[128:131], v[168:171], v[200:203], v[128:131]
	v_mfma_f32_16x16x32_bf16 v[124:127], v[176:179], v[200:203], v[124:127]
	v_mfma_f32_16x16x32_bf16 v[116:119], v[168:171], v[208:211], v[116:119]
	v_mfma_f32_16x16x32_bf16 v[108:111], v[176:179], v[208:211], v[108:111]
	v_mfma_f32_16x16x32_bf16 v[100:103], v[168:171], v[216:219], v[100:103]
	v_mfma_f32_16x16x32_bf16 v[92:95], v[176:179], v[216:219], v[92:95]
	v_mfma_f32_16x16x32_bf16 v[84:87], v[168:171], v[224:227], v[84:87]
	v_mfma_f32_16x16x32_bf16 v[76:79], v[176:179], v[224:227], v[76:79]
	v_mfma_f32_16x16x32_bf16 v[120:123], v[180:183], v[196:199], v[120:123]
	v_mfma_f32_16x16x32_bf16 v[112:115], v[188:191], v[196:199], v[112:115]
	v_mfma_f32_16x16x32_bf16 v[104:107], v[180:183], v[204:207], v[104:107]
	v_mfma_f32_16x16x32_bf16 v[96:99], v[188:191], v[204:207], v[96:99]
	v_mfma_f32_16x16x32_bf16 v[88:91], v[180:183], v[212:215], v[88:91]
	v_mfma_f32_16x16x32_bf16 v[80:83], v[188:191], v[212:215], v[80:83]
	v_mfma_f32_16x16x32_bf16 v[72:75], v[180:183], v[220:223], v[72:75]
	v_mfma_f32_16x16x32_bf16 v[68:71], v[188:191], v[220:223], v[68:71]
	v_mfma_f32_16x16x32_bf16 v[120:123], v[184:187], v[200:203], v[120:123]
	v_mfma_f32_16x16x32_bf16 v[112:115], v[192:195], v[200:203], v[112:115]
	v_mfma_f32_16x16x32_bf16 v[104:107], v[184:187], v[208:211], v[104:107]
	v_mfma_f32_16x16x32_bf16 v[96:99], v[192:195], v[208:211], v[96:99]
	v_mfma_f32_16x16x32_bf16 v[88:91], v[184:187], v[216:219], v[88:91]
	v_mfma_f32_16x16x32_bf16 v[80:83], v[192:195], v[216:219], v[80:83]
	v_mfma_f32_16x16x32_bf16 v[72:75], v[184:187], v[224:227], v[72:75]
	v_mfma_f32_16x16x32_bf16 v[68:71], v[192:195], v[224:227], v[68:71]
	s_setprio 0
	s_barrier
	s_add_i32 s33, s33, s10
	s_mov_b32 m0, s33
	ds_read_b128 v[196:199], v167 offset:49152
	ds_read_b128 v[200:203], v167 offset:50176
	ds_read_b128 v[204:207], v167 offset:51200
	ds_read_b128 v[208:211], v167 offset:52224
	ds_read_b128 v[212:215], v167 offset:53248
	ds_read_b128 v[216:219], v167 offset:54272
	ds_read_b128 v[220:223], v167 offset:55296
	ds_read_b128 v[224:227], v167 offset:56320
	s_add_u32 s100, s46, 0x80
	s_addc_u32 s101, s47, 0
	global_load_lds_dwordx4 v2, s[100:101]
	s_add_i32 m0, s33, 0x2000
	s_add_u32 s46, s46, 0x80080
	s_addc_u32 s47, s47, 0
	s_add_i32 s33, s43, s10
	s_add_u32 s100, s46, 0xfff80000
	s_addc_u32 s101, s47, -1
	global_load_lds_dwordx4 v0, s[100:101]
	s_mov_b32 m0, s33
	s_nop 0
	global_load_lds_dwordx4 v2, s[46:47]
	s_add_i32 m0, s33, 0x2000
	s_nop 0
	global_load_lds_dwordx4 v0, s[46:47]
	s_mov_b32 m0, s16
	s_nop 0
	s_add_u32 s100, s48, 0xfff80080
	s_addc_u32 s101, s49, -1
	global_load_lds_dwordx4 v134, s[100:101]
	s_mov_b32 m0, s17
	s_nop 0
	s_add_u32 s100, s48, 0xfff80080
	s_addc_u32 s101, s49, -1
	global_load_lds_dwordx4 v132, s[100:101]
	s_waitcnt vmcnt(8)
	s_waitcnt lgkmcnt(0)
	s_barrier
	s_setprio 1
	s_waitcnt lgkmcnt(0)
	v_mfma_f32_16x16x32_bf16 v[64:67], v[154:157], v[196:199], v[64:67]
	v_mfma_f32_16x16x32_bf16 v[60:63], v[172:175], v[196:199], v[60:63]
	v_mfma_f32_16x16x32_bf16 v[52:55], v[154:157], v[204:207], v[52:55]
	v_mfma_f32_16x16x32_bf16 v[44:47], v[172:175], v[204:207], v[44:47]
	v_mfma_f32_16x16x32_bf16 v[36:39], v[154:157], v[212:215], v[36:39]
	v_mfma_f32_16x16x32_bf16 v[28:31], v[172:175], v[212:215], v[28:31]
	v_mfma_f32_16x16x32_bf16 v[20:23], v[154:157], v[220:223], v[20:23]
	v_mfma_f32_16x16x32_bf16 v[12:15], v[172:175], v[220:223], v[12:15]
	v_mfma_f32_16x16x32_bf16 v[64:67], v[168:171], v[200:203], v[64:67]
	v_mfma_f32_16x16x32_bf16 v[60:63], v[176:179], v[200:203], v[60:63]
	v_mfma_f32_16x16x32_bf16 v[52:55], v[168:171], v[208:211], v[52:55]
	v_mfma_f32_16x16x32_bf16 v[44:47], v[176:179], v[208:211], v[44:47]
	v_mfma_f32_16x16x32_bf16 v[36:39], v[168:171], v[216:219], v[36:39]
	v_mfma_f32_16x16x32_bf16 v[28:31], v[176:179], v[216:219], v[28:31]
	v_mfma_f32_16x16x32_bf16 v[20:23], v[168:171], v[224:227], v[20:23]
	v_mfma_f32_16x16x32_bf16 v[12:15], v[176:179], v[224:227], v[12:15]
	v_mfma_f32_16x16x32_bf16 v[56:59], v[180:183], v[196:199], v[56:59]
	v_mfma_f32_16x16x32_bf16 v[48:51], v[188:191], v[196:199], v[48:51]
	v_mfma_f32_16x16x32_bf16 v[40:43], v[180:183], v[204:207], v[40:43]
	v_mfma_f32_16x16x32_bf16 v[32:35], v[188:191], v[204:207], v[32:35]
	v_mfma_f32_16x16x32_bf16 v[24:27], v[180:183], v[212:215], v[24:27]
	v_mfma_f32_16x16x32_bf16 v[16:19], v[188:191], v[212:215], v[16:19]
	v_mfma_f32_16x16x32_bf16 v[8:11], v[180:183], v[220:223], v[8:11]
	v_mfma_f32_16x16x32_bf16 v[4:7], v[188:191], v[220:223], v[4:7]
	v_mfma_f32_16x16x32_bf16 v[56:59], v[184:187], v[200:203], v[56:59]
	v_mfma_f32_16x16x32_bf16 v[48:51], v[192:195], v[200:203], v[48:51]
	v_mfma_f32_16x16x32_bf16 v[40:43], v[184:187], v[208:211], v[40:43]
	v_mfma_f32_16x16x32_bf16 v[32:35], v[192:195], v[208:211], v[32:35]
	v_mfma_f32_16x16x32_bf16 v[24:27], v[184:187], v[216:219], v[24:27]
	v_mfma_f32_16x16x32_bf16 v[16:19], v[192:195], v[216:219], v[16:19]
	v_mfma_f32_16x16x32_bf16 v[8:11], v[184:187], v[224:227], v[8:11]
	v_mfma_f32_16x16x32_bf16 v[4:7], v[192:195], v[224:227], v[4:7]
	s_setprio 0
	s_barrier
	s_add_i32 s35, s35, 2
	s_add_u32 s31, s31, 0x100
	s_addc_u32 s34, s34, 0
	s_add_u32 s44, s44, 0x100
	s_addc_u32 s45, s45, 0
	s_cmp_gt_u32 s35, 29
	s_cbranch_scc0 .LBB0_342
	s_and_b64 vcc, exec, s[22:23]
	s_cbranch_vccz .LBB0_345
	s_nop 0

.Lpj_scales_ready:
	s_movk_i32 s33, 0x3800
	v_mov_b64_e32 v[170:171], s[20:21]
	v_lshl_or_b32 v176, s30, 8, v163
	v_ashrrev_i32_e32 v177, 31, v176
	v_lshlrev_b64 v[176:177], 1, v[176:177]
	v_mad_i64_i32 v[204:205], s[28:29], v168, s33, v[170:171]
	v_mad_i64_i32 v[206:207], s[28:29], v164, s33, v[170:171]
	v_mad_i64_i32 v[208:209], s[28:29], v160, s33, v[170:171]
	v_mad_i64_i32 v[210:211], s[28:29], v156, s33, v[170:171]
	v_mad_i64_i32 v[212:213], s[28:29], v154, s33, v[170:171]
	v_mad_i64_i32 v[214:215], s[28:29], v150, s33, v[170:171]
	v_mad_i64_i32 v[216:217], s[28:29], v146, s33, v[170:171]
	v_mad_i64_i32 v[218:219], s[28:29], v142, s33, v[170:171]
	v_lshl_add_u64 v[204:205], v[204:205], 0, v[176:177]
	v_lshl_add_u64 v[206:207], v[206:207], 0, v[176:177]
	v_lshl_add_u64 v[208:209], v[208:209], 0, v[176:177]
	v_lshl_add_u64 v[210:211], v[210:211], 0, v[176:177]
	v_lshl_add_u64 v[212:213], v[212:213], 0, v[176:177]
	v_lshl_add_u64 v[214:215], v[214:215], 0, v[176:177]
	v_lshl_add_u64 v[216:217], v[216:217], 0, v[176:177]
	v_lshl_add_u64 v[218:219], v[218:219], 0, v[176:177]
	s_mov_b64 s[42:43], -1
	s_andn2_b64 vcc, exec, s[36:37]
	v_pk_mul_f32 v[128:129], v[128:129], v[228:229] op_sel_hi:[1,0]
	v_pk_mul_f32 v[130:131], v[130:131], v[228:229] op_sel_hi:[1,0]
	v_pk_mul_f32 v[124:125], v[124:125], v[228:229] op_sel_hi:[1,0]
	v_pk_mul_f32 v[126:127], v[126:127], v[228:229] op_sel_hi:[1,0]
	v_cvt_pk_bf16_f32 v128, v128, v129
	v_cvt_pk_bf16_f32 v129, v130, v131
	v_cvt_pk_bf16_f32 v130, v124, v125
	v_cvt_pk_bf16_f32 v131, v126, v127
	s_waitcnt vmcnt(0)
	global_store_dwordx4 v[204:205], v[128:131], off
	v_pk_mul_f32 v[120:121], v[120:121], v[228:229] op_sel_hi:[1,0]
	v_pk_mul_f32 v[122:123], v[122:123], v[228:229] op_sel_hi:[1,0]
	v_pk_mul_f32 v[112:113], v[112:113], v[228:229] op_sel_hi:[1,0]
	v_pk_mul_f32 v[114:115], v[114:115], v[228:229] op_sel_hi:[1,0]
	v_cvt_pk_bf16_f32 v120, v120, v121
	v_cvt_pk_bf16_f32 v121, v122, v123
	v_cvt_pk_bf16_f32 v122, v112, v113
	v_cvt_pk_bf16_f32 v123, v114, v115
	global_store_dwordx4 v[204:205], v[120:123], off offset:256
	v_pk_mul_f32 v[116:117], v[116:117], v[230:231] op_sel_hi:[1,0]
	v_pk_mul_f32 v[118:119], v[118:119], v[230:231] op_sel_hi:[1,0]
	v_pk_mul_f32 v[108:109], v[108:109], v[230:231] op_sel_hi:[1,0]
	v_pk_mul_f32 v[110:111], v[110:111], v[230:231] op_sel_hi:[1,0]
	v_cvt_pk_bf16_f32 v116, v116, v117
	v_cvt_pk_bf16_f32 v117, v118, v119
	v_cvt_pk_bf16_f32 v118, v108, v109
	v_cvt_pk_bf16_f32 v119, v110, v111
	global_store_dwordx4 v[206:207], v[116:119], off
	v_pk_mul_f32 v[104:105], v[104:105], v[230:231] op_sel_hi:[1,0]
	v_pk_mul_f32 v[106:107], v[106:107], v[230:231] op_sel_hi:[1,0]
	v_pk_mul_f32 v[96:97], v[96:97], v[230:231] op_sel_hi:[1,0]
	v_pk_mul_f32 v[98:99], v[98:99], v[230:231] op_sel_hi:[1,0]
	v_cvt_pk_bf16_f32 v104, v104, v105
	v_cvt_pk_bf16_f32 v105, v106, v107
	v_cvt_pk_bf16_f32 v106, v96, v97
	v_cvt_pk_bf16_f32 v107, v98, v99
	global_store_dwordx4 v[206:207], v[104:107], off offset:256
	v_pk_mul_f32 v[100:101], v[100:101], v[238:239] op_sel_hi:[1,0]
	v_pk_mul_f32 v[102:103], v[102:103], v[238:239] op_sel_hi:[1,0]
	v_pk_mul_f32 v[92:93], v[92:93], v[238:239] op_sel_hi:[1,0]
	v_pk_mul_f32 v[94:95], v[94:95], v[238:239] op_sel_hi:[1,0]
	v_cvt_pk_bf16_f32 v100, v100, v101
	v_cvt_pk_bf16_f32 v101, v102, v103
	v_cvt_pk_bf16_f32 v102, v92, v93
	v_cvt_pk_bf16_f32 v103, v94, v95
	global_store_dwordx4 v[208:209], v[100:103], off
	v_pk_mul_f32 v[88:89], v[88:89], v[238:239] op_sel_hi:[1,0]
	v_pk_mul_f32 v[90:91], v[90:91], v[238:239] op_sel_hi:[1,0]
	v_pk_mul_f32 v[80:81], v[80:81], v[238:239] op_sel_hi:[1,0]
	v_pk_mul_f32 v[82:83], v[82:83], v[238:239] op_sel_hi:[1,0]
	v_cvt_pk_bf16_f32 v88, v88, v89
	v_cvt_pk_bf16_f32 v89, v90, v91
	v_cvt_pk_bf16_f32 v90, v80, v81
	v_cvt_pk_bf16_f32 v91, v82, v83
	global_store_dwordx4 v[208:209], v[88:91], off offset:256
	v_pk_mul_f32 v[84:85], v[84:85], v[242:243] op_sel_hi:[1,0]
	v_pk_mul_f32 v[86:87], v[86:87], v[242:243] op_sel_hi:[1,0]
	v_pk_mul_f32 v[76:77], v[76:77], v[242:243] op_sel_hi:[1,0]
	v_pk_mul_f32 v[78:79], v[78:79], v[242:243] op_sel_hi:[1,0]
	v_cvt_pk_bf16_f32 v84, v84, v85
	v_cvt_pk_bf16_f32 v85, v86, v87
	v_cvt_pk_bf16_f32 v86, v76, v77
	v_cvt_pk_bf16_f32 v87, v78, v79
	global_store_dwordx4 v[210:211], v[84:87], off
	v_pk_mul_f32 v[72:73], v[72:73], v[242:243] op_sel_hi:[1,0]
	v_pk_mul_f32 v[74:75], v[74:75], v[242:243] op_sel_hi:[1,0]
	v_pk_mul_f32 v[68:69], v[68:69], v[242:243] op_sel_hi:[1,0]
	v_pk_mul_f32 v[70:71], v[70:71], v[242:243] op_sel_hi:[1,0]
	v_cvt_pk_bf16_f32 v72, v72, v73
	v_cvt_pk_bf16_f32 v73, v74, v75
	v_cvt_pk_bf16_f32 v74, v68, v69
	v_cvt_pk_bf16_f32 v75, v70, v71
	global_store_dwordx4 v[210:211], v[72:75], off offset:256
	v_pk_mul_f32 v[64:65], v[64:65], v[244:245] op_sel_hi:[1,0]
	v_pk_mul_f32 v[66:67], v[66:67], v[244:245] op_sel_hi:[1,0]
	v_pk_mul_f32 v[60:61], v[60:61], v[244:245] op_sel_hi:[1,0]
	v_pk_mul_f32 v[62:63], v[62:63], v[244:245] op_sel_hi:[1,0]
	v_cvt_pk_bf16_f32 v64, v64, v65
	v_cvt_pk_bf16_f32 v65, v66, v67
	v_cvt_pk_bf16_f32 v66, v60, v61
	v_cvt_pk_bf16_f32 v67, v62, v63
	global_store_dwordx4 v[212:213], v[64:67], off
	v_pk_mul_f32 v[56:57], v[56:57], v[244:245] op_sel_hi:[1,0]
	v_pk_mul_f32 v[58:59], v[58:59], v[244:245] op_sel_hi:[1,0]
	v_pk_mul_f32 v[48:49], v[48:49], v[244:245] op_sel_hi:[1,0]
	v_pk_mul_f32 v[50:51], v[50:51], v[244:245] op_sel_hi:[1,0]
	v_cvt_pk_bf16_f32 v56, v56, v57
	v_cvt_pk_bf16_f32 v57, v58, v59
	v_cvt_pk_bf16_f32 v58, v48, v49
	v_cvt_pk_bf16_f32 v59, v50, v51
	global_store_dwordx4 v[212:213], v[56:59], off offset:256
	v_pk_mul_f32 v[52:53], v[52:53], v[246:247] op_sel_hi:[1,0]
	v_pk_mul_f32 v[54:55], v[54:55], v[246:247] op_sel_hi:[1,0]
	v_pk_mul_f32 v[44:45], v[44:45], v[246:247] op_sel_hi:[1,0]
	v_pk_mul_f32 v[46:47], v[46:47], v[246:247] op_sel_hi:[1,0]
	v_cvt_pk_bf16_f32 v52, v52, v53
	v_cvt_pk_bf16_f32 v53, v54, v55
	v_cvt_pk_bf16_f32 v54, v44, v45
	v_cvt_pk_bf16_f32 v55, v46, v47
	global_store_dwordx4 v[214:215], v[52:55], off
	v_pk_mul_f32 v[40:41], v[40:41], v[246:247] op_sel_hi:[1,0]
	v_pk_mul_f32 v[42:43], v[42:43], v[246:247] op_sel_hi:[1,0]
	v_pk_mul_f32 v[32:33], v[32:33], v[246:247] op_sel_hi:[1,0]
	v_pk_mul_f32 v[34:35], v[34:35], v[246:247] op_sel_hi:[1,0]
	v_cvt_pk_bf16_f32 v40, v40, v41
	v_cvt_pk_bf16_f32 v41, v42, v43
	v_cvt_pk_bf16_f32 v42, v32, v33
	v_cvt_pk_bf16_f32 v43, v34, v35
	global_store_dwordx4 v[214:215], v[40:43], off offset:256
	v_pk_mul_f32 v[36:37], v[36:37], v[248:249] op_sel_hi:[1,0]
	v_pk_mul_f32 v[38:39], v[38:39], v[248:249] op_sel_hi:[1,0]
	v_pk_mul_f32 v[28:29], v[28:29], v[248:249] op_sel_hi:[1,0]
	v_pk_mul_f32 v[30:31], v[30:31], v[248:249] op_sel_hi:[1,0]
	v_cvt_pk_bf16_f32 v36, v36, v37
	v_cvt_pk_bf16_f32 v37, v38, v39
	v_cvt_pk_bf16_f32 v38, v28, v29
	v_cvt_pk_bf16_f32 v39, v30, v31
	global_store_dwordx4 v[216:217], v[36:39], off
	v_pk_mul_f32 v[24:25], v[24:25], v[248:249] op_sel_hi:[1,0]
	v_pk_mul_f32 v[26:27], v[26:27], v[248:249] op_sel_hi:[1,0]
	v_pk_mul_f32 v[16:17], v[16:17], v[248:249] op_sel_hi:[1,0]
	v_pk_mul_f32 v[18:19], v[18:19], v[248:249] op_sel_hi:[1,0]
	v_cvt_pk_bf16_f32 v24, v24, v25
	v_cvt_pk_bf16_f32 v25, v26, v27
	v_cvt_pk_bf16_f32 v26, v16, v17
	v_cvt_pk_bf16_f32 v27, v18, v19
	global_store_dwordx4 v[216:217], v[24:27], off offset:256
	v_pk_mul_f32 v[20:21], v[20:21], v[250:251] op_sel_hi:[1,0]
	v_pk_mul_f32 v[22:23], v[22:23], v[250:251] op_sel_hi:[1,0]
	v_pk_mul_f32 v[12:13], v[12:13], v[250:251] op_sel_hi:[1,0]
	v_pk_mul_f32 v[14:15], v[14:15], v[250:251] op_sel_hi:[1,0]
	v_cvt_pk_bf16_f32 v20, v20, v21
	v_cvt_pk_bf16_f32 v21, v22, v23
	v_cvt_pk_bf16_f32 v22, v12, v13
	v_cvt_pk_bf16_f32 v23, v14, v15
	global_store_dwordx4 v[218:219], v[20:23], off
	v_pk_mul_f32 v[8:9], v[8:9], v[250:251] op_sel_hi:[1,0]
	v_pk_mul_f32 v[10:11], v[10:11], v[250:251] op_sel_hi:[1,0]
	v_pk_mul_f32 v[4:5], v[4:5], v[250:251] op_sel_hi:[1,0]
	v_pk_mul_f32 v[6:7], v[6:7], v[250:251] op_sel_hi:[1,0]
	v_cvt_pk_bf16_f32 v8, v8, v9
	v_cvt_pk_bf16_f32 v9, v10, v11
	v_cvt_pk_bf16_f32 v10, v4, v5
	v_cvt_pk_bf16_f32 v11, v6, v7
	global_store_dwordx4 v[218:219], v[8:11], off offset:256
	s_cbranch_vccnz .LBB0_338
	s_andn2_b64 vcc, exec, s[2:3]
	s_cbranch_vccnz .LBB0_337
	s_nop 0
	s_branch .LBB0_337
.LBB0_348:
	s_waitcnt vmcnt(0)
	s_and_b64 vcc, exec, s[22:23]
	s_cbranch_vccz .Lpj_noextra
	s_barrier
.Lpj_noextra:
	s_barrier
.LBB0_349:
	v_readlane_b32 s2, v254, 58
	s_or_b32 s4, s2, 4
	v_readlane_b32 s2, v253, 12
	v_readlane_b32 s3, v253, 13
	s_cmp_lt_i32 s4, s3
	s_cselect_b64 s[2:3], -1, 0
	s_and_b64 s[0:1], s[0:1], s[2:3]
	s_andn2_b64 vcc, exec, s[0:1]
	s_cbranch_vccnz .LBB0_399
	s_waitcnt vmcnt(0)
	s_barrier
	s_mov_b64 s[0:1], exec
	v_readlane_b32 s6, v253, 31
	v_readlane_b32 s7, v253, 32
	v_readlane_b32 s10, v254, 54
	v_readlane_b32 s8, v254, 56
	s_and_b64 s[6:7], s[0:1], s[6:7]
	v_readlane_b32 s11, v254, 55
	v_readlane_b32 s9, v254, 57
	s_mov_b64 exec, s[6:7]
	s_cbranch_execz .LBB0_398
	v_readlane_b32 s5, v253, 14
	s_waitcnt vmcnt(0) expcnt(0) lgkmcnt(0)
	s_nop 0
	v_mov_b32_e32 v0, s5
	ds_read_b32 v2, v0
	ds_read_b32 v0, v0 offset:4
	s_waitcnt lgkmcnt(1)
	v_cmp_ne_u32_e32 vcc, 0, v2
	s_cbranch_vccnz .LBB0_366
	s_load_dwordx2 s[6:7], s[58:59], 0x0
	s_load_dword s5, s[58:59], 0x8
	s_waitcnt lgkmcnt(0)
	s_mul_i32 s6, s7, s6
	s_mul_i32 s5, s6, s5
	s_mov_b32 s6, 1
	s_branch .LBB0_354

.LBB0_1066:
	s_add_u32 s12, s44, 0xfff80080
	s_addc_u32 s13, s45, -1
	s_add_i32 s14, 0, 0x10000
	s_cmp_eq_u32 s11, 28
	s_cselect_b32 s49, s5, s13
	s_cselect_b32 s48, s6, s12
	s_cselect_b32 s47, s7, s10
	s_cselect_b32 s46, s8, s9
	s_add_i32 s15, 0, 0x14000
	v_add_u32_e32 v154, s14, v163
	v_add_u32_e32 v158, s15, v163
	ds_read_b128 v[142:145], v154
	ds_read_b128 v[146:149], v154 offset:1024
	ds_read_b128 v[150:153], v154 offset:2048
	ds_read_b128 v[154:157], v154 offset:3072
	ds_read_b128 v[168:171], v158
	ds_read_b128 v[172:175], v158 offset:1024
	ds_read_b128 v[176:179], v158 offset:2048
	ds_read_b128 v[180:183], v158 offset:3072
	s_add_i32 m0, s60, 0xc000
	ds_read_b128 v[184:187], v167
	ds_read_b128 v[188:191], v167 offset:1024
	ds_read_b128 v[192:195], v167 offset:2048
	ds_read_b128 v[196:199], v167 offset:3072
	ds_read_b128 v[200:203], v167 offset:4096
	ds_read_b128 v[204:207], v167 offset:5120
	ds_read_b128 v[208:211], v167 offset:6144
	ds_read_b128 v[212:215], v167 offset:7168
	global_load_lds_dwordx4 v140, s[44:45]
	s_add_i32 m0, s60, 0xe000
	s_nop 0
	global_load_lds_dwordx4 v138, s[44:45]
	s_waitcnt vmcnt(8)
	s_waitcnt lgkmcnt(0)
	s_barrier
	s_setprio 1
	s_waitcnt lgkmcnt(0)
	v_mfma_f32_16x16x32_bf16 v[124:127], v[142:145], v[184:187], v[124:127]
	v_mfma_f32_16x16x32_bf16 v[120:123], v[150:153], v[184:187], v[120:123]
	v_mfma_f32_16x16x32_bf16 v[112:115], v[142:145], v[192:195], v[112:115]
	v_mfma_f32_16x16x32_bf16 v[104:107], v[150:153], v[192:195], v[104:107]
	v_mfma_f32_16x16x32_bf16 v[96:99], v[142:145], v[200:203], v[96:99]
	v_mfma_f32_16x16x32_bf16 v[88:91], v[150:153], v[200:203], v[88:91]
	v_mfma_f32_16x16x32_bf16 v[80:83], v[142:145], v[208:211], v[80:83]
	v_mfma_f32_16x16x32_bf16 v[72:75], v[150:153], v[208:211], v[72:75]
	v_mfma_f32_16x16x32_bf16 v[124:127], v[146:149], v[188:191], v[124:127]
	v_mfma_f32_16x16x32_bf16 v[120:123], v[154:157], v[188:191], v[120:123]
	v_mfma_f32_16x16x32_bf16 v[112:115], v[146:149], v[196:199], v[112:115]
	v_mfma_f32_16x16x32_bf16 v[104:107], v[154:157], v[196:199], v[104:107]
	v_mfma_f32_16x16x32_bf16 v[96:99], v[146:149], v[204:207], v[96:99]
	v_mfma_f32_16x16x32_bf16 v[88:91], v[154:157], v[204:207], v[88:91]
	v_mfma_f32_16x16x32_bf16 v[80:83], v[146:149], v[212:215], v[80:83]
	v_mfma_f32_16x16x32_bf16 v[72:75], v[154:157], v[212:215], v[72:75]
	v_mfma_f32_16x16x32_bf16 v[128:131], v[168:171], v[184:187], v[128:131]
	v_mfma_f32_16x16x32_bf16 v[116:119], v[176:179], v[184:187], v[116:119]
	v_mfma_f32_16x16x32_bf16 v[108:111], v[168:171], v[192:195], v[108:111]
	v_mfma_f32_16x16x32_bf16 v[100:103], v[176:179], v[192:195], v[100:103]
	v_mfma_f32_16x16x32_bf16 v[92:95], v[168:171], v[200:203], v[92:95]
	v_mfma_f32_16x16x32_bf16 v[84:87], v[176:179], v[200:203], v[84:87]
	v_mfma_f32_16x16x32_bf16 v[76:79], v[168:171], v[208:211], v[76:79]
	v_mfma_f32_16x16x32_bf16 v[68:71], v[176:179], v[208:211], v[68:71]
	v_mfma_f32_16x16x32_bf16 v[128:131], v[172:175], v[188:191], v[128:131]
	v_mfma_f32_16x16x32_bf16 v[116:119], v[180:183], v[188:191], v[116:119]
	v_mfma_f32_16x16x32_bf16 v[108:111], v[172:175], v[196:199], v[108:111]
	v_mfma_f32_16x16x32_bf16 v[100:103], v[180:183], v[196:199], v[100:103]
	v_mfma_f32_16x16x32_bf16 v[92:95], v[172:175], v[204:207], v[92:95]
	v_mfma_f32_16x16x32_bf16 v[84:87], v[180:183], v[204:207], v[84:87]
	v_mfma_f32_16x16x32_bf16 v[76:79], v[172:175], v[212:215], v[76:79]
	v_mfma_f32_16x16x32_bf16 v[68:71], v[180:183], v[212:215], v[68:71]
	s_setprio 0
	s_barrier
	s_add_i32 s12, s14, s56
	s_mov_b32 m0, s12
	ds_read_b128 v[184:187], v167 offset:16384
	ds_read_b128 v[188:191], v167 offset:17408
	ds_read_b128 v[192:195], v167 offset:18432
	ds_read_b128 v[196:199], v167 offset:19456
	ds_read_b128 v[200:203], v167 offset:20480
	ds_read_b128 v[204:207], v167 offset:21504
	ds_read_b128 v[208:211], v167 offset:22528
	ds_read_b128 v[212:215], v167 offset:23552
	global_load_lds_dwordx4 v2, s[46:47]
	s_add_i32 m0, s12, 0x2000
	s_add_u32 s12, s46, 0x80000
	s_addc_u32 s13, s47, 0
	s_add_i32 s14, s15, s56
	global_load_lds_dwordx4 v0, s[46:47]
	s_mov_b32 m0, s14
	s_nop 0
	global_load_lds_dwordx4 v2, s[12:13]
	s_add_i32 m0, s14, 0x2000
	s_nop 0
	global_load_lds_dwordx4 v0, s[12:13]
	s_mov_b32 m0, s60
	s_nop 0
	global_load_lds_dwordx4 v134, s[48:49]
	s_mov_b32 m0, s61
	s_nop 0
	global_load_lds_dwordx4 v132, s[48:49]
	s_waitcnt vmcnt(8)
	s_waitcnt lgkmcnt(0)
	s_barrier
	s_setprio 1
	s_waitcnt lgkmcnt(0)
	v_mfma_f32_16x16x32_bf16 v[64:67], v[142:145], v[184:187], v[64:67]
	v_mfma_f32_16x16x32_bf16 v[56:59], v[150:153], v[184:187], v[56:59]
	v_mfma_f32_16x16x32_bf16 v[48:51], v[142:145], v[192:195], v[48:51]
	v_mfma_f32_16x16x32_bf16 v[40:43], v[150:153], v[192:195], v[40:43]
	v_mfma_f32_16x16x32_bf16 v[32:35], v[142:145], v[200:203], v[32:35]
	v_mfma_f32_16x16x32_bf16 v[24:27], v[150:153], v[200:203], v[24:27]
	v_mfma_f32_16x16x32_bf16 v[16:19], v[142:145], v[208:211], v[16:19]
	v_mfma_f32_16x16x32_bf16 v[8:11], v[150:153], v[208:211], v[8:11]
	v_mfma_f32_16x16x32_bf16 v[64:67], v[146:149], v[188:191], v[64:67]
	v_mfma_f32_16x16x32_bf16 v[56:59], v[154:157], v[188:191], v[56:59]
	v_mfma_f32_16x16x32_bf16 v[48:51], v[146:149], v[196:199], v[48:51]
	v_mfma_f32_16x16x32_bf16 v[40:43], v[154:157], v[196:199], v[40:43]
	v_mfma_f32_16x16x32_bf16 v[32:35], v[146:149], v[204:207], v[32:35]
	v_mfma_f32_16x16x32_bf16 v[24:27], v[154:157], v[204:207], v[24:27]
	v_mfma_f32_16x16x32_bf16 v[16:19], v[146:149], v[212:215], v[16:19]
	v_mfma_f32_16x16x32_bf16 v[8:11], v[154:157], v[212:215], v[8:11]
	v_mfma_f32_16x16x32_bf16 v[60:63], v[168:171], v[184:187], v[60:63]
	v_mfma_f32_16x16x32_bf16 v[52:55], v[176:179], v[184:187], v[52:55]
	v_mfma_f32_16x16x32_bf16 v[44:47], v[168:171], v[192:195], v[44:47]
	v_mfma_f32_16x16x32_bf16 v[36:39], v[176:179], v[192:195], v[36:39]
	v_mfma_f32_16x16x32_bf16 v[28:31], v[168:171], v[200:203], v[28:31]
	v_mfma_f32_16x16x32_bf16 v[20:23], v[176:179], v[200:203], v[20:23]
	v_mfma_f32_16x16x32_bf16 v[12:15], v[168:171], v[208:211], v[12:15]
	v_mfma_f32_16x16x32_bf16 v[4:7], v[176:179], v[208:211], v[4:7]
	v_mfma_f32_16x16x32_bf16 v[60:63], v[172:175], v[188:191], v[60:63]
	v_mfma_f32_16x16x32_bf16 v[52:55], v[180:183], v[188:191], v[52:55]
	v_mfma_f32_16x16x32_bf16 v[44:47], v[172:175], v[196:199], v[44:47]
	v_mfma_f32_16x16x32_bf16 v[36:39], v[180:183], v[196:199], v[36:39]
	v_mfma_f32_16x16x32_bf16 v[28:31], v[172:175], v[204:207], v[28:31]
	v_mfma_f32_16x16x32_bf16 v[20:23], v[180:183], v[204:207], v[20:23]
	v_mfma_f32_16x16x32_bf16 v[12:15], v[172:175], v[212:215], v[12:15]
	v_mfma_f32_16x16x32_bf16 v[4:7], v[180:183], v[212:215], v[4:7]
	s_setprio 0
	s_barrier
	s_add_i32 s14, 0, 0x18000
	s_add_i32 s15, 0, 0x1c000
	v_add_u32_e32 v154, s14, v163
	v_add_u32_e32 v160, s15, v163
	ds_read_b128 v[142:145], v154
	ds_read_b128 v[146:149], v154 offset:1024
	ds_read_b128 v[150:153], v154 offset:2048
	ds_read_b128 v[154:157], v154 offset:3072
	ds_read_b128 v[168:171], v160
	ds_read_b128 v[172:175], v160 offset:1024
	ds_read_b128 v[176:179], v160 offset:2048
	ds_read_b128 v[180:183], v160 offset:3072
	s_add_u32 s12, s48, 0x80000
	s_addc_u32 s13, s49, 0
	s_mov_b32 m0, s62
	ds_read_b128 v[184:187], v167 offset:32768
	ds_read_b128 v[188:191], v167 offset:33792
	ds_read_b128 v[192:195], v167 offset:34816
	ds_read_b128 v[196:199], v167 offset:35840
	ds_read_b128 v[200:203], v167 offset:36864
	ds_read_b128 v[204:207], v167 offset:37888
	ds_read_b128 v[208:211], v167 offset:38912
	ds_read_b128 v[212:215], v167 offset:39936
	global_load_lds_dwordx4 v134, s[12:13]
	s_mov_b32 m0, s63
	s_nop 0
	global_load_lds_dwordx4 v132, s[12:13]
	s_waitcnt vmcnt(8)
	s_waitcnt lgkmcnt(0)
	s_barrier
	s_setprio 1
	s_waitcnt lgkmcnt(0)
	v_mfma_f32_16x16x32_bf16 v[124:127], v[142:145], v[184:187], v[124:127]
	v_mfma_f32_16x16x32_bf16 v[120:123], v[150:153], v[184:187], v[120:123]
	v_mfma_f32_16x16x32_bf16 v[112:115], v[142:145], v[192:195], v[112:115]
	v_mfma_f32_16x16x32_bf16 v[104:107], v[150:153], v[192:195], v[104:107]
	v_mfma_f32_16x16x32_bf16 v[96:99], v[142:145], v[200:203], v[96:99]
	v_mfma_f32_16x16x32_bf16 v[88:91], v[150:153], v[200:203], v[88:91]
	v_mfma_f32_16x16x32_bf16 v[80:83], v[142:145], v[208:211], v[80:83]
	v_mfma_f32_16x16x32_bf16 v[72:75], v[150:153], v[208:211], v[72:75]
	v_mfma_f32_16x16x32_bf16 v[124:127], v[146:149], v[188:191], v[124:127]
	v_mfma_f32_16x16x32_bf16 v[120:123], v[154:157], v[188:191], v[120:123]
	v_mfma_f32_16x16x32_bf16 v[112:115], v[146:149], v[196:199], v[112:115]
	v_mfma_f32_16x16x32_bf16 v[104:107], v[154:157], v[196:199], v[104:107]
	v_mfma_f32_16x16x32_bf16 v[96:99], v[146:149], v[204:207], v[96:99]
	v_mfma_f32_16x16x32_bf16 v[88:91], v[154:157], v[204:207], v[88:91]
	v_mfma_f32_16x16x32_bf16 v[80:83], v[146:149], v[212:215], v[80:83]
	v_mfma_f32_16x16x32_bf16 v[72:75], v[154:157], v[212:215], v[72:75]
	v_mfma_f32_16x16x32_bf16 v[128:131], v[168:171], v[184:187], v[128:131]
	v_mfma_f32_16x16x32_bf16 v[116:119], v[176:179], v[184:187], v[116:119]
	v_mfma_f32_16x16x32_bf16 v[108:111], v[168:171], v[192:195], v[108:111]
	v_mfma_f32_16x16x32_bf16 v[100:103], v[176:179], v[192:195], v[100:103]
	v_mfma_f32_16x16x32_bf16 v[92:95], v[168:171], v[200:203], v[92:95]
	v_mfma_f32_16x16x32_bf16 v[84:87], v[176:179], v[200:203], v[84:87]
	v_mfma_f32_16x16x32_bf16 v[76:79], v[168:171], v[208:211], v[76:79]
	v_mfma_f32_16x16x32_bf16 v[68:71], v[176:179], v[208:211], v[68:71]
	v_mfma_f32_16x16x32_bf16 v[128:131], v[172:175], v[188:191], v[128:131]
	v_mfma_f32_16x16x32_bf16 v[116:119], v[180:183], v[188:191], v[116:119]
	v_mfma_f32_16x16x32_bf16 v[108:111], v[172:175], v[196:199], v[108:111]
	v_mfma_f32_16x16x32_bf16 v[100:103], v[180:183], v[196:199], v[100:103]
	v_mfma_f32_16x16x32_bf16 v[92:95], v[172:175], v[204:207], v[92:95]
	v_mfma_f32_16x16x32_bf16 v[84:87], v[180:183], v[204:207], v[84:87]
	v_mfma_f32_16x16x32_bf16 v[76:79], v[172:175], v[212:215], v[76:79]
	v_mfma_f32_16x16x32_bf16 v[68:71], v[180:183], v[212:215], v[68:71]
	s_setprio 0
	s_barrier
	s_add_i32 s12, s14, s56
	s_mov_b32 m0, s12
	ds_read_b128 v[184:187], v167 offset:49152
	ds_read_b128 v[188:191], v167 offset:50176
	ds_read_b128 v[192:195], v167 offset:51200
	ds_read_b128 v[196:199], v167 offset:52224
	ds_read_b128 v[200:203], v167 offset:53248
	ds_read_b128 v[204:207], v167 offset:54272
	ds_read_b128 v[208:211], v167 offset:55296
	ds_read_b128 v[212:215], v167 offset:56320
	s_add_u32 s100, s46, 0x80
	s_addc_u32 s101, s47, 0
	global_load_lds_dwordx4 v2, s[100:101]
	s_add_i32 m0, s12, 0x2000
	s_add_u32 s12, s46, 0x80080
	s_addc_u32 s13, s47, 0
	s_add_i32 s14, s15, s56
	s_add_u32 s100, s46, 0x80
	s_addc_u32 s101, s47, 0
	global_load_lds_dwordx4 v0, s[100:101]
	s_mov_b32 m0, s14
	s_nop 0
	global_load_lds_dwordx4 v2, s[12:13]
	s_add_i32 m0, s14, 0x2000
	s_nop 0
	global_load_lds_dwordx4 v0, s[12:13]
	s_mov_b32 m0, s64
	s_nop 0
	s_add_u32 s100, s48, 0x80
	s_addc_u32 s101, s49, 0
	global_load_lds_dwordx4 v134, s[100:101]
	s_mov_b32 m0, s65
	s_nop 0
	s_add_u32 s100, s48, 0x80
	s_addc_u32 s101, s49, 0
	global_load_lds_dwordx4 v132, s[100:101]
	s_waitcnt vmcnt(8)
	s_waitcnt lgkmcnt(0)
	s_barrier
	s_setprio 1
	s_waitcnt lgkmcnt(0)
	v_mfma_f32_16x16x32_bf16 v[64:67], v[142:145], v[184:187], v[64:67]
	v_mfma_f32_16x16x32_bf16 v[56:59], v[150:153], v[184:187], v[56:59]
	v_mfma_f32_16x16x32_bf16 v[48:51], v[142:145], v[192:195], v[48:51]
	v_mfma_f32_16x16x32_bf16 v[40:43], v[150:153], v[192:195], v[40:43]
	v_mfma_f32_16x16x32_bf16 v[32:35], v[142:145], v[200:203], v[32:35]
	v_mfma_f32_16x16x32_bf16 v[24:27], v[150:153], v[200:203], v[24:27]
	v_mfma_f32_16x16x32_bf16 v[16:19], v[142:145], v[208:211], v[16:19]
	v_mfma_f32_16x16x32_bf16 v[8:11], v[150:153], v[208:211], v[8:11]
	v_mfma_f32_16x16x32_bf16 v[64:67], v[146:149], v[188:191], v[64:67]
	v_mfma_f32_16x16x32_bf16 v[56:59], v[154:157], v[188:191], v[56:59]
	v_mfma_f32_16x16x32_bf16 v[48:51], v[146:149], v[196:199], v[48:51]
	v_mfma_f32_16x16x32_bf16 v[40:43], v[154:157], v[196:199], v[40:43]
	v_mfma_f32_16x16x32_bf16 v[32:35], v[146:149], v[204:207], v[32:35]
	v_mfma_f32_16x16x32_bf16 v[24:27], v[154:157], v[204:207], v[24:27]
	v_mfma_f32_16x16x32_bf16 v[16:19], v[146:149], v[212:215], v[16:19]
	v_mfma_f32_16x16x32_bf16 v[8:11], v[154:157], v[212:215], v[8:11]
	v_mfma_f32_16x16x32_bf16 v[60:63], v[168:171], v[184:187], v[60:63]
	v_mfma_f32_16x16x32_bf16 v[52:55], v[176:179], v[184:187], v[52:55]
	v_mfma_f32_16x16x32_bf16 v[44:47], v[168:171], v[192:195], v[44:47]
	v_mfma_f32_16x16x32_bf16 v[36:39], v[176:179], v[192:195], v[36:39]
	v_mfma_f32_16x16x32_bf16 v[28:31], v[168:171], v[200:203], v[28:31]
	v_mfma_f32_16x16x32_bf16 v[20:23], v[176:179], v[200:203], v[20:23]
	v_mfma_f32_16x16x32_bf16 v[12:15], v[168:171], v[208:211], v[12:15]
	v_mfma_f32_16x16x32_bf16 v[4:7], v[176:179], v[208:211], v[4:7]
	v_mfma_f32_16x16x32_bf16 v[60:63], v[172:175], v[188:191], v[60:63]
	v_mfma_f32_16x16x32_bf16 v[52:55], v[180:183], v[188:191], v[52:55]
	v_mfma_f32_16x16x32_bf16 v[44:47], v[172:175], v[196:199], v[44:47]
	v_mfma_f32_16x16x32_bf16 v[36:39], v[180:183], v[196:199], v[36:39]
	v_mfma_f32_16x16x32_bf16 v[28:31], v[172:175], v[204:207], v[28:31]
	v_mfma_f32_16x16x32_bf16 v[20:23], v[180:183], v[204:207], v[20:23]
	v_mfma_f32_16x16x32_bf16 v[12:15], v[172:175], v[212:215], v[12:15]
	v_mfma_f32_16x16x32_bf16 v[4:7], v[180:183], v[212:215], v[4:7]
	s_setprio 0
	s_barrier
	s_add_i32 s11, s11, 2
	s_add_u32 s9, s9, 0x100
	s_addc_u32 s10, s10, 0
	s_add_u32 s44, s44, 0x100
	s_addc_u32 s45, s45, 0
	s_cmp_gt_u32 s11, 29
	s_cbranch_scc0 .LBB0_1066
	s_and_b64 vcc, exec, s[22:23]
	s_cbranch_vccz .LBB0_1069
	s_nop 0

.Lgu_scales_ready:
	v_lshl_or_b32 v158, s4, 7, v166
	v_ashrrev_i32_e32 v159, 31, v158
	v_lshlrev_b64 v[158:159], 1, v[158:159]
	v_mov_b64_e32 v[154:155], s[20:21]
	s_movk_i32 s6, 0x2c00
	v_mad_i64_i32 v[202:203], s[4:5], v142, s6, v[154:155]
	v_mad_i64_i32 v[204:205], s[4:5], v143, s6, v[154:155]
	v_mad_i64_i32 v[206:207], s[4:5], v144, s6, v[154:155]
	v_mad_i64_i32 v[208:209], s[4:5], v145, s6, v[154:155]
	v_mad_i64_i32 v[210:211], s[4:5], v146, s6, v[154:155]
	v_mad_i64_i32 v[212:213], s[4:5], v147, s6, v[154:155]
	v_mad_i64_i32 v[214:215], s[4:5], v148, s6, v[154:155]
	v_mad_i64_i32 v[216:217], s[4:5], v149, s6, v[154:155]
	v_lshl_add_u64 v[202:203], v[202:203], 0, v[158:159]
	v_lshl_add_u64 v[204:205], v[204:205], 0, v[158:159]
	v_lshl_add_u64 v[206:207], v[206:207], 0, v[158:159]
	v_lshl_add_u64 v[208:209], v[208:209], 0, v[158:159]
	v_lshl_add_u64 v[210:211], v[210:211], 0, v[158:159]
	v_lshl_add_u64 v[212:213], v[212:213], 0, v[158:159]
	v_lshl_add_u64 v[214:215], v[214:215], 0, v[158:159]
	v_lshl_add_u64 v[216:217], v[216:217], 0, v[158:159]
	s_mov_b64 s[42:43], -1
	s_andn2_b64 vcc, exec, s[36:37]
	v_mul_f32_e32 v150, v228, v228
	v_mul_f32_e32 v152, 0xbfb8aa3b, v228
	v_pk_mul_f32 v[218:219], v[124:125], v[152:153] op_sel_hi:[1,0]
	v_pk_mul_f32 v[220:221], v[126:127], v[152:153] op_sel_hi:[1,0]
	v_pk_mul_f32 v[222:223], v[120:121], v[152:153] op_sel_hi:[1,0]
	v_pk_mul_f32 v[224:225], v[122:123], v[152:153] op_sel_hi:[1,0]
	v_exp_f32_e32 v218, v218
	v_exp_f32_e32 v219, v219
	v_exp_f32_e32 v220, v220
	v_exp_f32_e32 v221, v221
	v_exp_f32_e32 v222, v222
	v_exp_f32_e32 v223, v223
	v_exp_f32_e32 v224, v224
	v_exp_f32_e32 v225, v225
	v_pk_add_f32 v[218:219], v[218:219], 1.0 op_sel_hi:[1,0]
	v_pk_add_f32 v[220:221], v[220:221], 1.0 op_sel_hi:[1,0]
	v_pk_add_f32 v[222:223], v[222:223], 1.0 op_sel_hi:[1,0]
	v_pk_add_f32 v[224:225], v[224:225], 1.0 op_sel_hi:[1,0]
	v_rcp_f32_e32 v218, v218
	v_rcp_f32_e32 v219, v219
	v_rcp_f32_e32 v220, v220
	v_rcp_f32_e32 v221, v221
	v_rcp_f32_e32 v222, v222
	v_rcp_f32_e32 v223, v223
	v_rcp_f32_e32 v224, v224
	v_rcp_f32_e32 v225, v225
	v_pk_mul_f32 v[124:125], v[124:125], v[128:129]
	v_pk_mul_f32 v[126:127], v[126:127], v[130:131]
	v_pk_mul_f32 v[120:121], v[120:121], v[116:117]
	v_pk_mul_f32 v[122:123], v[122:123], v[118:119]
	v_pk_mul_f32 v[124:125], v[124:125], v[150:151] op_sel_hi:[1,0]
	v_pk_mul_f32 v[126:127], v[126:127], v[150:151] op_sel_hi:[1,0]
	v_pk_mul_f32 v[120:121], v[120:121], v[150:151] op_sel_hi:[1,0]
	v_pk_mul_f32 v[122:123], v[122:123], v[150:151] op_sel_hi:[1,0]
	v_pk_mul_f32 v[124:125], v[124:125], v[218:219]
	v_pk_mul_f32 v[126:127], v[126:127], v[220:221]
	v_pk_mul_f32 v[120:121], v[120:121], v[222:223]
	v_pk_mul_f32 v[122:123], v[122:123], v[224:225]
	v_cvt_pk_bf16_f32 v124, v124, v125
	v_cvt_pk_bf16_f32 v125, v126, v127
	v_cvt_pk_bf16_f32 v126, v120, v121
	v_cvt_pk_bf16_f32 v127, v122, v123
	s_waitcnt vmcnt(0)
	global_store_dwordx4 v[202:203], v[124:127], off
	v_mul_f32_e32 v150, v230, v230
	v_mul_f32_e32 v152, 0xbfb8aa3b, v230
	v_pk_mul_f32 v[218:219], v[112:113], v[152:153] op_sel_hi:[1,0]
	v_pk_mul_f32 v[220:221], v[114:115], v[152:153] op_sel_hi:[1,0]
	v_pk_mul_f32 v[222:223], v[104:105], v[152:153] op_sel_hi:[1,0]
	v_pk_mul_f32 v[224:225], v[106:107], v[152:153] op_sel_hi:[1,0]
	v_exp_f32_e32 v218, v218
	v_exp_f32_e32 v219, v219
	v_exp_f32_e32 v220, v220
	v_exp_f32_e32 v221, v221
	v_exp_f32_e32 v222, v222
	v_exp_f32_e32 v223, v223
	v_exp_f32_e32 v224, v224
	v_exp_f32_e32 v225, v225
	v_pk_add_f32 v[218:219], v[218:219], 1.0 op_sel_hi:[1,0]
	v_pk_add_f32 v[220:221], v[220:221], 1.0 op_sel_hi:[1,0]
	v_pk_add_f32 v[222:223], v[222:223], 1.0 op_sel_hi:[1,0]
	v_pk_add_f32 v[224:225], v[224:225], 1.0 op_sel_hi:[1,0]
	v_rcp_f32_e32 v218, v218
	v_rcp_f32_e32 v219, v219
	v_rcp_f32_e32 v220, v220
	v_rcp_f32_e32 v221, v221
	v_rcp_f32_e32 v222, v222
	v_rcp_f32_e32 v223, v223
	v_rcp_f32_e32 v224, v224
	v_rcp_f32_e32 v225, v225
	v_pk_mul_f32 v[112:113], v[112:113], v[108:109]
	v_pk_mul_f32 v[114:115], v[114:115], v[110:111]
	v_pk_mul_f32 v[104:105], v[104:105], v[100:101]
	v_pk_mul_f32 v[106:107], v[106:107], v[102:103]
	v_pk_mul_f32 v[112:113], v[112:113], v[150:151] op_sel_hi:[1,0]
	v_pk_mul_f32 v[114:115], v[114:115], v[150:151] op_sel_hi:[1,0]
	v_pk_mul_f32 v[104:105], v[104:105], v[150:151] op_sel_hi:[1,0]
	v_pk_mul_f32 v[106:107], v[106:107], v[150:151] op_sel_hi:[1,0]
	v_pk_mul_f32 v[112:113], v[112:113], v[218:219]
	v_pk_mul_f32 v[114:115], v[114:115], v[220:221]
	v_pk_mul_f32 v[104:105], v[104:105], v[222:223]
	v_pk_mul_f32 v[106:107], v[106:107], v[224:225]
	v_cvt_pk_bf16_f32 v112, v112, v113
	v_cvt_pk_bf16_f32 v113, v114, v115
	v_cvt_pk_bf16_f32 v114, v104, v105
	v_cvt_pk_bf16_f32 v115, v106, v107
	global_store_dwordx4 v[204:205], v[112:115], off
	v_mul_f32_e32 v150, v238, v238
	v_mul_f32_e32 v152, 0xbfb8aa3b, v238
	v_pk_mul_f32 v[218:219], v[96:97], v[152:153] op_sel_hi:[1,0]
	v_pk_mul_f32 v[220:221], v[98:99], v[152:153] op_sel_hi:[1,0]
	v_pk_mul_f32 v[222:223], v[88:89], v[152:153] op_sel_hi:[1,0]
	v_pk_mul_f32 v[224:225], v[90:91], v[152:153] op_sel_hi:[1,0]
	v_exp_f32_e32 v218, v218
	v_exp_f32_e32 v219, v219
	v_exp_f32_e32 v220, v220
	v_exp_f32_e32 v221, v221
	v_exp_f32_e32 v222, v222
	v_exp_f32_e32 v223, v223
	v_exp_f32_e32 v224, v224
	v_exp_f32_e32 v225, v225
	v_pk_add_f32 v[218:219], v[218:219], 1.0 op_sel_hi:[1,0]
	v_pk_add_f32 v[220:221], v[220:221], 1.0 op_sel_hi:[1,0]
	v_pk_add_f32 v[222:223], v[222:223], 1.0 op_sel_hi:[1,0]
	v_pk_add_f32 v[224:225], v[224:225], 1.0 op_sel_hi:[1,0]
	v_rcp_f32_e32 v218, v218
	v_rcp_f32_e32 v219, v219
	v_rcp_f32_e32 v220, v220
	v_rcp_f32_e32 v221, v221
	v_rcp_f32_e32 v222, v222
	v_rcp_f32_e32 v223, v223
	v_rcp_f32_e32 v224, v224
	v_rcp_f32_e32 v225, v225
	v_pk_mul_f32 v[96:97], v[96:97], v[92:93]
	v_pk_mul_f32 v[98:99], v[98:99], v[94:95]
	v_pk_mul_f32 v[88:89], v[88:89], v[84:85]
	v_pk_mul_f32 v[90:91], v[90:91], v[86:87]
	v_pk_mul_f32 v[96:97], v[96:97], v[150:151] op_sel_hi:[1,0]
	v_pk_mul_f32 v[98:99], v[98:99], v[150:151] op_sel_hi:[1,0]
	v_pk_mul_f32 v[88:89], v[88:89], v[150:151] op_sel_hi:[1,0]
	v_pk_mul_f32 v[90:91], v[90:91], v[150:151] op_sel_hi:[1,0]
	v_pk_mul_f32 v[96:97], v[96:97], v[218:219]
	v_pk_mul_f32 v[98:99], v[98:99], v[220:221]
	v_pk_mul_f32 v[88:89], v[88:89], v[222:223]
	v_pk_mul_f32 v[90:91], v[90:91], v[224:225]
	v_cvt_pk_bf16_f32 v96, v96, v97
	v_cvt_pk_bf16_f32 v97, v98, v99
	v_cvt_pk_bf16_f32 v98, v88, v89
	v_cvt_pk_bf16_f32 v99, v90, v91
	global_store_dwordx4 v[206:207], v[96:99], off
	v_mul_f32_e32 v150, v242, v242
	v_mul_f32_e32 v152, 0xbfb8aa3b, v242
	v_pk_mul_f32 v[218:219], v[80:81], v[152:153] op_sel_hi:[1,0]
	v_pk_mul_f32 v[220:221], v[82:83], v[152:153] op_sel_hi:[1,0]
	v_pk_mul_f32 v[222:223], v[72:73], v[152:153] op_sel_hi:[1,0]
	v_pk_mul_f32 v[224:225], v[74:75], v[152:153] op_sel_hi:[1,0]
	v_exp_f32_e32 v218, v218
	v_exp_f32_e32 v219, v219
	v_exp_f32_e32 v220, v220
	v_exp_f32_e32 v221, v221
	v_exp_f32_e32 v222, v222
	v_exp_f32_e32 v223, v223
	v_exp_f32_e32 v224, v224
	v_exp_f32_e32 v225, v225
	v_pk_add_f32 v[218:219], v[218:219], 1.0 op_sel_hi:[1,0]
	v_pk_add_f32 v[220:221], v[220:221], 1.0 op_sel_hi:[1,0]
	v_pk_add_f32 v[222:223], v[222:223], 1.0 op_sel_hi:[1,0]
	v_pk_add_f32 v[224:225], v[224:225], 1.0 op_sel_hi:[1,0]
	v_rcp_f32_e32 v218, v218
	v_rcp_f32_e32 v219, v219
	v_rcp_f32_e32 v220, v220
	v_rcp_f32_e32 v221, v221
	v_rcp_f32_e32 v222, v222
	v_rcp_f32_e32 v223, v223
	v_rcp_f32_e32 v224, v224
	v_rcp_f32_e32 v225, v225
	v_pk_mul_f32 v[80:81], v[80:81], v[76:77]
	v_pk_mul_f32 v[82:83], v[82:83], v[78:79]
	v_pk_mul_f32 v[72:73], v[72:73], v[68:69]
	v_pk_mul_f32 v[74:75], v[74:75], v[70:71]
	v_pk_mul_f32 v[80:81], v[80:81], v[150:151] op_sel_hi:[1,0]
	v_pk_mul_f32 v[82:83], v[82:83], v[150:151] op_sel_hi:[1,0]
	v_pk_mul_f32 v[72:73], v[72:73], v[150:151] op_sel_hi:[1,0]
	v_pk_mul_f32 v[74:75], v[74:75], v[150:151] op_sel_hi:[1,0]
	v_pk_mul_f32 v[80:81], v[80:81], v[218:219]
	v_pk_mul_f32 v[82:83], v[82:83], v[220:221]
	v_pk_mul_f32 v[72:73], v[72:73], v[222:223]
	v_pk_mul_f32 v[74:75], v[74:75], v[224:225]
	v_cvt_pk_bf16_f32 v80, v80, v81
	v_cvt_pk_bf16_f32 v81, v82, v83
	v_cvt_pk_bf16_f32 v82, v72, v73
	v_cvt_pk_bf16_f32 v83, v74, v75
	global_store_dwordx4 v[208:209], v[80:83], off
	v_mul_f32_e32 v150, v244, v244
	v_mul_f32_e32 v152, 0xbfb8aa3b, v244
	v_pk_mul_f32 v[218:219], v[64:65], v[152:153] op_sel_hi:[1,0]
	v_pk_mul_f32 v[220:221], v[66:67], v[152:153] op_sel_hi:[1,0]
	v_pk_mul_f32 v[222:223], v[56:57], v[152:153] op_sel_hi:[1,0]
	v_pk_mul_f32 v[224:225], v[58:59], v[152:153] op_sel_hi:[1,0]
	v_exp_f32_e32 v218, v218
	v_exp_f32_e32 v219, v219
	v_exp_f32_e32 v220, v220
	v_exp_f32_e32 v221, v221
	v_exp_f32_e32 v222, v222
	v_exp_f32_e32 v223, v223
	v_exp_f32_e32 v224, v224
	v_exp_f32_e32 v225, v225
	v_pk_add_f32 v[218:219], v[218:219], 1.0 op_sel_hi:[1,0]
	v_pk_add_f32 v[220:221], v[220:221], 1.0 op_sel_hi:[1,0]
	v_pk_add_f32 v[222:223], v[222:223], 1.0 op_sel_hi:[1,0]
	v_pk_add_f32 v[224:225], v[224:225], 1.0 op_sel_hi:[1,0]
	v_rcp_f32_e32 v218, v218
	v_rcp_f32_e32 v219, v219
	v_rcp_f32_e32 v220, v220
	v_rcp_f32_e32 v221, v221
	v_rcp_f32_e32 v222, v222
	v_rcp_f32_e32 v223, v223
	v_rcp_f32_e32 v224, v224
	v_rcp_f32_e32 v225, v225
	v_pk_mul_f32 v[64:65], v[64:65], v[60:61]
	v_pk_mul_f32 v[66:67], v[66:67], v[62:63]
	v_pk_mul_f32 v[56:57], v[56:57], v[52:53]
	v_pk_mul_f32 v[58:59], v[58:59], v[54:55]
	v_pk_mul_f32 v[64:65], v[64:65], v[150:151] op_sel_hi:[1,0]
	v_pk_mul_f32 v[66:67], v[66:67], v[150:151] op_sel_hi:[1,0]
	v_pk_mul_f32 v[56:57], v[56:57], v[150:151] op_sel_hi:[1,0]
	v_pk_mul_f32 v[58:59], v[58:59], v[150:151] op_sel_hi:[1,0]
	v_pk_mul_f32 v[64:65], v[64:65], v[218:219]
	v_pk_mul_f32 v[66:67], v[66:67], v[220:221]
	v_pk_mul_f32 v[56:57], v[56:57], v[222:223]
	v_pk_mul_f32 v[58:59], v[58:59], v[224:225]
	v_cvt_pk_bf16_f32 v64, v64, v65
	v_cvt_pk_bf16_f32 v65, v66, v67
	v_cvt_pk_bf16_f32 v66, v56, v57
	v_cvt_pk_bf16_f32 v67, v58, v59
	global_store_dwordx4 v[210:211], v[64:67], off
	v_mul_f32_e32 v150, v246, v246
	v_mul_f32_e32 v152, 0xbfb8aa3b, v246
	v_pk_mul_f32 v[218:219], v[48:49], v[152:153] op_sel_hi:[1,0]
	v_pk_mul_f32 v[220:221], v[50:51], v[152:153] op_sel_hi:[1,0]
	v_pk_mul_f32 v[222:223], v[40:41], v[152:153] op_sel_hi:[1,0]
	v_pk_mul_f32 v[224:225], v[42:43], v[152:153] op_sel_hi:[1,0]
	v_exp_f32_e32 v218, v218
	v_exp_f32_e32 v219, v219
	v_exp_f32_e32 v220, v220
	v_exp_f32_e32 v221, v221
	v_exp_f32_e32 v222, v222
	v_exp_f32_e32 v223, v223
	v_exp_f32_e32 v224, v224
	v_exp_f32_e32 v225, v225
	v_pk_add_f32 v[218:219], v[218:219], 1.0 op_sel_hi:[1,0]
	v_pk_add_f32 v[220:221], v[220:221], 1.0 op_sel_hi:[1,0]
	v_pk_add_f32 v[222:223], v[222:223], 1.0 op_sel_hi:[1,0]
	v_pk_add_f32 v[224:225], v[224:225], 1.0 op_sel_hi:[1,0]
	v_rcp_f32_e32 v218, v218
	v_rcp_f32_e32 v219, v219
	v_rcp_f32_e32 v220, v220
	v_rcp_f32_e32 v221, v221
	v_rcp_f32_e32 v222, v222
	v_rcp_f32_e32 v223, v223
	v_rcp_f32_e32 v224, v224
	v_rcp_f32_e32 v225, v225
	v_pk_mul_f32 v[48:49], v[48:49], v[44:45]
	v_pk_mul_f32 v[50:51], v[50:51], v[46:47]
	v_pk_mul_f32 v[40:41], v[40:41], v[36:37]
	v_pk_mul_f32 v[42:43], v[42:43], v[38:39]
	v_pk_mul_f32 v[48:49], v[48:49], v[150:151] op_sel_hi:[1,0]
	v_pk_mul_f32 v[50:51], v[50:51], v[150:151] op_sel_hi:[1,0]
	v_pk_mul_f32 v[40:41], v[40:41], v[150:151] op_sel_hi:[1,0]
	v_pk_mul_f32 v[42:43], v[42:43], v[150:151] op_sel_hi:[1,0]
	v_pk_mul_f32 v[48:49], v[48:49], v[218:219]
	v_pk_mul_f32 v[50:51], v[50:51], v[220:221]
	v_pk_mul_f32 v[40:41], v[40:41], v[222:223]
	v_pk_mul_f32 v[42:43], v[42:43], v[224:225]
	v_cvt_pk_bf16_f32 v48, v48, v49
	v_cvt_pk_bf16_f32 v49, v50, v51
	v_cvt_pk_bf16_f32 v50, v40, v41
	v_cvt_pk_bf16_f32 v51, v42, v43
	global_store_dwordx4 v[212:213], v[48:51], off
	v_mul_f32_e32 v150, v248, v248
	v_mul_f32_e32 v152, 0xbfb8aa3b, v248
	v_pk_mul_f32 v[218:219], v[32:33], v[152:153] op_sel_hi:[1,0]
	v_pk_mul_f32 v[220:221], v[34:35], v[152:153] op_sel_hi:[1,0]
	v_pk_mul_f32 v[222:223], v[24:25], v[152:153] op_sel_hi:[1,0]
	v_pk_mul_f32 v[224:225], v[26:27], v[152:153] op_sel_hi:[1,0]
	v_exp_f32_e32 v218, v218
	v_exp_f32_e32 v219, v219
	v_exp_f32_e32 v220, v220
	v_exp_f32_e32 v221, v221
	v_exp_f32_e32 v222, v222
	v_exp_f32_e32 v223, v223
	v_exp_f32_e32 v224, v224
	v_exp_f32_e32 v225, v225
	v_pk_add_f32 v[218:219], v[218:219], 1.0 op_sel_hi:[1,0]
	v_pk_add_f32 v[220:221], v[220:221], 1.0 op_sel_hi:[1,0]
	v_pk_add_f32 v[222:223], v[222:223], 1.0 op_sel_hi:[1,0]
	v_pk_add_f32 v[224:225], v[224:225], 1.0 op_sel_hi:[1,0]
	v_rcp_f32_e32 v218, v218
	v_rcp_f32_e32 v219, v219
	v_rcp_f32_e32 v220, v220
	v_rcp_f32_e32 v221, v221
	v_rcp_f32_e32 v222, v222
	v_rcp_f32_e32 v223, v223
	v_rcp_f32_e32 v224, v224
	v_rcp_f32_e32 v225, v225
	v_pk_mul_f32 v[32:33], v[32:33], v[28:29]
	v_pk_mul_f32 v[34:35], v[34:35], v[30:31]
	v_pk_mul_f32 v[24:25], v[24:25], v[20:21]
	v_pk_mul_f32 v[26:27], v[26:27], v[22:23]
	v_pk_mul_f32 v[32:33], v[32:33], v[150:151] op_sel_hi:[1,0]
	v_pk_mul_f32 v[34:35], v[34:35], v[150:151] op_sel_hi:[1,0]
	v_pk_mul_f32 v[24:25], v[24:25], v[150:151] op_sel_hi:[1,0]
	v_pk_mul_f32 v[26:27], v[26:27], v[150:151] op_sel_hi:[1,0]
	v_pk_mul_f32 v[32:33], v[32:33], v[218:219]
	v_pk_mul_f32 v[34:35], v[34:35], v[220:221]
	v_pk_mul_f32 v[24:25], v[24:25], v[222:223]
	v_pk_mul_f32 v[26:27], v[26:27], v[224:225]
	v_cvt_pk_bf16_f32 v32, v32, v33
	v_cvt_pk_bf16_f32 v33, v34, v35
	v_cvt_pk_bf16_f32 v34, v24, v25
	v_cvt_pk_bf16_f32 v35, v26, v27
	global_store_dwordx4 v[214:215], v[32:35], off
	v_mul_f32_e32 v150, v250, v250
	v_mul_f32_e32 v152, 0xbfb8aa3b, v250
	v_pk_mul_f32 v[218:219], v[16:17], v[152:153] op_sel_hi:[1,0]
	v_pk_mul_f32 v[220:221], v[18:19], v[152:153] op_sel_hi:[1,0]
	v_pk_mul_f32 v[222:223], v[8:9], v[152:153] op_sel_hi:[1,0]
	v_pk_mul_f32 v[224:225], v[10:11], v[152:153] op_sel_hi:[1,0]
	v_exp_f32_e32 v218, v218
	v_exp_f32_e32 v219, v219
	v_exp_f32_e32 v220, v220
	v_exp_f32_e32 v221, v221
	v_exp_f32_e32 v222, v222
	v_exp_f32_e32 v223, v223
	v_exp_f32_e32 v224, v224
	v_exp_f32_e32 v225, v225
	v_pk_add_f32 v[218:219], v[218:219], 1.0 op_sel_hi:[1,0]
	v_pk_add_f32 v[220:221], v[220:221], 1.0 op_sel_hi:[1,0]
	v_pk_add_f32 v[222:223], v[222:223], 1.0 op_sel_hi:[1,0]
	v_pk_add_f32 v[224:225], v[224:225], 1.0 op_sel_hi:[1,0]
	v_rcp_f32_e32 v218, v218
	v_rcp_f32_e32 v219, v219
	v_rcp_f32_e32 v220, v220
	v_rcp_f32_e32 v221, v221
	v_rcp_f32_e32 v222, v222
	v_rcp_f32_e32 v223, v223
	v_rcp_f32_e32 v224, v224
	v_rcp_f32_e32 v225, v225
	v_pk_mul_f32 v[16:17], v[16:17], v[12:13]
	v_pk_mul_f32 v[18:19], v[18:19], v[14:15]
	v_pk_mul_f32 v[8:9], v[8:9], v[4:5]
	v_pk_mul_f32 v[10:11], v[10:11], v[6:7]
	v_pk_mul_f32 v[16:17], v[16:17], v[150:151] op_sel_hi:[1,0]
	v_pk_mul_f32 v[18:19], v[18:19], v[150:151] op_sel_hi:[1,0]
	v_pk_mul_f32 v[8:9], v[8:9], v[150:151] op_sel_hi:[1,0]
	v_pk_mul_f32 v[10:11], v[10:11], v[150:151] op_sel_hi:[1,0]
	v_pk_mul_f32 v[16:17], v[16:17], v[218:219]
	v_pk_mul_f32 v[18:19], v[18:19], v[220:221]
	v_pk_mul_f32 v[8:9], v[8:9], v[222:223]
	v_pk_mul_f32 v[10:11], v[10:11], v[224:225]
	v_cvt_pk_bf16_f32 v16, v16, v17
	v_cvt_pk_bf16_f32 v17, v18, v19
	v_cvt_pk_bf16_f32 v18, v8, v9
	v_cvt_pk_bf16_f32 v19, v10, v11
	global_store_dwordx4 v[216:217], v[16:19], off
	s_cbranch_vccnz .LBB0_1062
	s_andn2_b64 vcc, exec, s[2:3]
	s_cbranch_vccnz .LBB0_1061
	s_nop 0
	s_branch .LBB0_1061

.Lgu_noextra:
	s_barrier
.LBB0_1073:
	v_readlane_b32 s2, v254, 58
	s_add_i32 s4, s2, 10
	v_readlane_b32 s2, v253, 12
	v_readlane_b32 s3, v253, 13
	s_cmp_lt_i32 s4, s3
	s_cselect_b64 s[2:3], -1, 0
	s_and_b64 s[0:1], s[0:1], s[2:3]
	s_andn2_b64 vcc, exec, s[0:1]
	s_cbranch_vccnz .LBB0_1123
	s_waitcnt vmcnt(0)
	s_barrier
	s_mov_b64 s[0:1], exec
	v_readlane_b32 s6, v253, 31
	v_readlane_b32 s7, v253, 32
	s_and_b64 s[6:7], s[0:1], s[6:7]
	s_mov_b64 exec, s[6:7]
	s_cbranch_execz .LBB0_1122
	v_readlane_b32 s5, v253, 14
	s_waitcnt vmcnt(0) expcnt(0) lgkmcnt(0)
	s_nop 0
	v_mov_b32_e32 v0, s5
	ds_read_b32 v2, v0
	ds_read_b32 v0, v0 offset:4
	s_waitcnt lgkmcnt(1)
	v_cmp_ne_u32_e32 vcc, 0, v2
	s_cbranch_vccnz .LBB0_1090
	s_load_dwordx2 s[6:7], s[58:59], 0x0
	s_load_dword s5, s[58:59], 0x8
	s_waitcnt lgkmcnt(0)
	s_mul_i32 s6, s7, s6
	s_mul_i32 s5, s6, s5
	s_mov_b32 s6, 1
	s_branch .LBB0_1078
